# GDN scan: all 16 R-seed u16 reads issued at the chunk top into their final registers
# baseline (speedup 1.0000x reference)
.LBB0_709:
	ds_read_b128 v[128:131], v161 offset:18432
	ds_read_b128 v[174:177], v161 offset:18496
	ds_read_b128 v[178:181], v161 offset:23040
	ds_read_b128 v[182:185], v161 offset:23104
	ds_read_b128 v[186:189], v161 offset:27648
	ds_read_b128 v[190:193], v161 offset:27712
	ds_read_b128 v[194:197], v161 offset:32256
	ds_read_b128 v[202:205], v161 offset:32320
	ds_read_b128 v[206:209], v161 offset:18560
	ds_read_b128 v[210:213], v161 offset:18624
	ds_read_b128 v[214:217], v161 offset:23168
	ds_read_b128 v[218:221], v161 offset:23232
	ds_read_b128 v[222:225], v161 offset:27776
	ds_read_b128 v[226:229], v161 offset:27840
	ds_read_b128 v[230:233], v161 offset:32384
	ds_read_b128 v[234:237], v161 offset:32448
	ds_read_u16 v238, v170 offset:36864
	ds_read_u16 v239, v170 offset:37152
	ds_read_u16 v240, v170 offset:37440
	ds_read_u16 v241, v170 offset:37728
	ds_read_u16 v242, v170 offset:41472
	ds_read_u16 v243, v170 offset:41760
	ds_read_u16 v244, v170 offset:42048
	ds_read_u16 v245, v170 offset:42336
	ds_read_u16 v246, v170 offset:46080
	ds_read_u16 v247, v170 offset:46368
	ds_read_u16 v248, v170 offset:46656
	ds_read_u16 v249, v170 offset:46944
	ds_read_u16 v250, v170 offset:50688
	ds_read_u16 v251, v170 offset:50976
	ds_read_u16 v252, v170 offset:51264
	ds_read_u16 v253, v170 offset:51552
	s_cmp_lg_u32 s0, 1
	s_cselect_b64 s[8:9], -1, 0
	s_cmp_eq_u32 s0, 1
	v_lshl_add_u64 v[72:73], s[92:93], 0, v[122:123]
	s_cbranch_scc1 .LBB0_711
	v_lshl_add_u64 v[16:17], s[92:93], 0, v[124:125]
	v_add_co_u32_e32 v4, vcc, 0x1a004000, v16
	v_lshl_add_u64 v[24:25], s[92:93], 0, v[126:127]
	s_nop 0
	v_addc_co_u32_e32 v5, vcc, 0, v17, vcc
	v_add_co_u32_e32 v12, vcc, 0x1c004000, v16
	s_add_u32 s10, s92, s17
	s_nop 0
	v_addc_co_u32_e32 v13, vcc, 0, v17, vcc
	v_add_co_u32_e32 v20, vcc, 0x1e004000, v16
	s_addc_u32 s11, s93, s18
	s_nop 0
	v_addc_co_u32_e32 v21, vcc, 0, v17, vcc
	v_add_co_u32_e32 v28, vcc, 0x2058000, v24
	global_load_dwordx4 v[0:3], v[4:5], off
	s_nop 0
	global_load_dwordx4 v[4:7], v[4:5], off offset:16
	v_addc_co_u32_e32 v29, vcc, 0, v25, vcc
	v_add_co_u32_e32 v36, vcc, 0x2058000, v72
	global_load_dwordx4 v[8:11], v[12:13], off
	s_nop 0
	global_load_dwordx4 v[12:15], v[12:13], off offset:16
	v_addc_co_u32_e32 v37, vcc, 0, v73, vcc
	global_load_dwordx4 v[16:19], v[20:21], off
	s_nop 0
	global_load_dwordx4 v[20:23], v[20:21], off offset:16
	s_nop 0
	global_load_dwordx4 v[24:27], v[28:29], off offset:1152
	s_nop 0
	global_load_dwordx4 v[28:31], v[28:29], off offset:1280
	s_nop 0
	global_load_dwordx4 v[32:35], v[36:37], off offset:2176
	s_nop 0
	global_load_dwordx4 v[36:39], v[36:37], off offset:2192
	s_nop 0
	global_load_dword v172, v103, s[10:11]
.LBB0_711:
	v_add_co_u32_e32 v72, vcc, 0x2001000, v72
	v_cvt_pk_bf16_f32 v92, v52, v53
	s_nop 0
	v_addc_co_u32_e32 v73, vcc, 0, v73, vcc
	global_load_dwordx4 v[76:79], v[72:73], off offset:128
	s_nop 0
	global_load_dwordx4 v[72:75], v[72:73], off offset:144
	v_cvt_pk_bf16_f32 v93, v54, v55
	v_cvt_pk_bf16_f32 v94, v48, v49
	v_cvt_pk_bf16_f32 v95, v50, v51
	v_cvt_pk_bf16_f32 v88, v44, v45
	v_cvt_pk_bf16_f32 v89, v46, v47
	v_cvt_pk_bf16_f32 v90, v40, v41
	v_cvt_pk_bf16_f32 v91, v42, v43
	v_cvt_pk_bf16_f32 v84, v60, v61
	v_cvt_pk_bf16_f32 v85, v62, v63
	v_cvt_pk_bf16_f32 v86, v56, v57
	v_cvt_pk_bf16_f32 v87, v58, v59
	v_cvt_pk_bf16_f32 v80, v64, v65
	v_cvt_pk_bf16_f32 v81, v66, v67
	v_cvt_pk_bf16_f32 v82, v68, v69
	v_cvt_pk_bf16_f32 v83, v70, v71
	s_waitcnt lgkmcnt(0)
	v_lshlrev_b32_e32 v238, 16, v238
	v_lshlrev_b32_e32 v239, 16, v239
	v_lshlrev_b32_e32 v240, 16, v240
	v_lshlrev_b32_e32 v241, 16, v241
	v_lshlrev_b32_e32 v242, 16, v242
	v_lshlrev_b32_e32 v243, 16, v243
	v_lshlrev_b32_e32 v244, 16, v244
	v_lshlrev_b32_e32 v245, 16, v245
	v_lshlrev_b32_e32 v246, 16, v246
	v_lshlrev_b32_e32 v247, 16, v247
	v_lshlrev_b32_e32 v248, 16, v248
	v_lshlrev_b32_e32 v249, 16, v249
	v_lshlrev_b32_e32 v250, 16, v250
	v_lshlrev_b32_e32 v251, 16, v251
	v_lshlrev_b32_e32 v252, 16, v252
	v_lshlrev_b32_e32 v253, 16, v253
	v_mfma_f32_16x16x32_bf16 v[128:131], v[128:131], v[92:95], v[238:241]
	v_mfma_f32_16x16x32_bf16 v[178:181], v[178:181], v[92:95], v[242:245]
	v_mfma_f32_16x16x32_bf16 v[186:189], v[186:189], v[92:95], v[246:249]
	v_mfma_f32_16x16x32_bf16 v[194:197], v[194:197], v[92:95], v[250:253]
	v_mfma_f32_16x16x32_bf16 v[128:131], v[174:177], v[88:91], v[128:131]
	v_mfma_f32_16x16x32_bf16 v[174:177], v[182:185], v[88:91], v[178:181]
	v_mfma_f32_16x16x32_bf16 v[178:181], v[190:193], v[88:91], v[186:189]
	v_mfma_f32_16x16x32_bf16 v[182:185], v[202:205], v[88:91], v[194:197]
	s_nop 2
	ds_read_b128 v[186:189], v161
	ds_read_b128 v[190:193], v161 offset:64
	ds_read_b128 v[194:197], v161 offset:4608
	ds_read_b128 v[202:205], v161 offset:4672
	ds_read_b128 v[238:241], v161 offset:9216
	ds_read_b128 v[242:245], v161 offset:9280
	ds_read_b128 v[246:249], v161 offset:13824
	ds_read_b128 v[250:253], v161 offset:13888
	v_mfma_f32_16x16x32_bf16 v[128:131], v[206:209], v[84:87], v[128:131]
	v_mfma_f32_16x16x32_bf16 v[174:177], v[214:217], v[84:87], v[174:177]
	v_mfma_f32_16x16x32_bf16 v[178:181], v[222:225], v[84:87], v[178:181]
	v_mfma_f32_16x16x32_bf16 v[182:185], v[230:233], v[84:87], v[182:185]
	v_mfma_f32_16x16x32_bf16 v[128:131], v[210:213], v[80:83], v[128:131]
	v_mfma_f32_16x16x32_bf16 v[174:177], v[218:221], v[80:83], v[174:177]
	v_mfma_f32_16x16x32_bf16 v[178:181], v[226:229], v[80:83], v[178:181]
	v_mfma_f32_16x16x32_bf16 v[182:185], v[234:237], v[80:83], v[182:185]
	ds_read_b128 v[206:209], v161 offset:128
	ds_read_b128 v[210:213], v161 offset:192
	ds_read_b128 v[214:217], v161 offset:4736
	ds_read_b128 v[218:221], v161 offset:4800
	ds_read_b128 v[222:225], v161 offset:9344
	ds_read_b128 v[226:229], v161 offset:9408
	ds_read_b128 v[230:233], v161 offset:13952
	ds_read_b128 v[234:237], v161 offset:14016
	v_cvt_pk_bf16_f32 v128, v128, v129
	v_cvt_pk_bf16_f32 v129, v130, v131
	v_cvt_pk_bf16_f32 v130, v174, v175
	v_cvt_pk_bf16_f32 v131, v176, v177
	v_cvt_pk_bf16_f32 v174, v178, v179
	v_cvt_pk_bf16_f32 v175, v180, v181
	v_cvt_pk_bf16_f32 v176, v182, v183
	v_cvt_pk_bf16_f32 v177, v184, v185
	s_waitcnt lgkmcnt(14)
	v_mfma_f32_16x16x32_bf16 v[178:181], v[186:189], v[92:95], 0
	s_waitcnt lgkmcnt(13)
	v_mfma_f32_16x16x32_bf16 v[182:185], v[194:197], v[92:95], 0
	s_waitcnt lgkmcnt(11)
	v_mfma_f32_16x16x32_bf16 v[186:189], v[238:241], v[92:95], 0
	s_waitcnt lgkmcnt(9)
	v_mfma_f32_16x16x32_bf16 v[92:95], v[246:249], v[92:95], 0
	v_mfma_f32_16x16x32_bf16 v[178:181], v[190:193], v[88:91], v[178:181]
	v_mfma_f32_16x16x32_bf16 v[182:185], v[202:205], v[88:91], v[182:185]
	v_mfma_f32_16x16x32_bf16 v[186:189], v[242:245], v[88:91], v[186:189]
	s_waitcnt lgkmcnt(8)
	v_mfma_f32_16x16x32_bf16 v[88:91], v[250:253], v[88:91], v[92:95]
	s_nop 2
	ds_read_b128 v[92:95], v132
	ds_read_b128 v[190:193], v138
	ds_read_b128 v[194:197], v139
	ds_read_b128 v[202:205], v140
	ds_read_b128 v[238:241], v141
	ds_read_b128 v[242:245], v142
	ds_read_b128 v[246:249], v143
	ds_read_b128 v[250:253], v144
	s_waitcnt lgkmcnt(14)
	v_mfma_f32_16x16x32_bf16 v[178:181], v[206:209], v[84:87], v[178:181]
	s_waitcnt lgkmcnt(13)
	v_mfma_f32_16x16x32_bf16 v[182:185], v[214:217], v[84:87], v[182:185]
	s_waitcnt lgkmcnt(11)
	v_mfma_f32_16x16x32_bf16 v[186:189], v[222:225], v[84:87], v[186:189]
	s_waitcnt lgkmcnt(9)
	v_mfma_f32_16x16x32_bf16 v[84:87], v[230:233], v[84:87], v[88:91]
	v_mfma_f32_16x16x32_bf16 v[88:91], v[210:213], v[80:83], v[178:181]
	v_mfma_f32_16x16x32_bf16 v[178:181], v[218:221], v[80:83], v[182:185]
	s_nop 2
	ds_read_b128 v[182:185], v133
	ds_read_b128 v[206:209], v145
	ds_read_b128 v[210:213], v146
	ds_read_b128 v[214:217], v147
	v_mfma_f32_16x16x32_bf16 v[186:189], v[226:229], v[80:83], v[186:189]
	ds_read_b128 v[218:221], v148
	ds_read_b128 v[222:225], v149
	ds_read_b128 v[226:229], v150
	ds_read_b128 v[230:233], v151
	s_waitcnt lgkmcnt(14)
	v_mfma_f32_16x16x32_bf16 v[80:83], v[234:237], v[80:83], v[84:87]
	v_mfma_f32_16x16x32_bf16 v[84:87], v[92:95], v[128:131], 0
	s_waitcnt lgkmcnt(13)
	v_mfma_f32_16x16x32_bf16 v[92:95], v[194:197], v[128:131], 0
	s_waitcnt lgkmcnt(11)
	v_mfma_f32_16x16x32_bf16 v[194:197], v[238:241], v[128:131], 0
	s_waitcnt lgkmcnt(9)
	v_mfma_f32_16x16x32_bf16 v[128:131], v[246:249], v[128:131], 0
	v_mfma_f32_16x16x32_bf16 v[84:87], v[190:193], v[174:177], v[84:87]
	v_mfma_f32_16x16x32_bf16 v[92:95], v[202:205], v[174:177], v[92:95]
	v_mfma_f32_16x16x32_bf16 v[190:193], v[242:245], v[174:177], v[194:197]
	s_waitcnt lgkmcnt(8)
	v_mfma_f32_16x16x32_bf16 v[128:131], v[250:253], v[174:177], v[128:131]
	ds_read_b128 v[174:177], v119 offset:55296
	ds_read_b128 v[194:197], v119 offset:55360
	ds_read_b128 v[202:205], v119 offset:57856
	ds_read_b128 v[234:237], v119 offset:57920
	ds_read_b128 v[238:241], v119 offset:60416
	ds_read_b128 v[242:245], v119 offset:60480
	ds_read_b128 v[246:249], v119 offset:62976
	ds_read_b128 v[250:253], v119 offset:63040
	v_cvt_pk_bf16_f32 v104, v84, v85
	v_cvt_pk_bf16_f32 v105, v86, v87
	v_cvt_pk_bf16_f32 v106, v92, v93
	v_cvt_pk_bf16_f32 v107, v94, v95
	v_cvt_pk_bf16_f32 v94, v128, v129
	v_cvt_pk_bf16_f32 v95, v130, v131
	s_waitcnt lgkmcnt(14)
	v_mfma_f32_16x16x32_bf16 v[84:87], v[182:185], v[104:107], v[88:91]
	v_cvt_pk_bf16_f32 v92, v190, v191
	v_cvt_pk_bf16_f32 v93, v192, v193
	v_pk_mul_f32 v[54:55], v[54:55], v[118:119] op_sel_hi:[1,0]
	s_waitcnt lgkmcnt(13)
	v_mfma_f32_16x16x32_bf16 v[88:91], v[210:213], v[104:107], v[178:181]
	v_mul_f32_e64 v52, v52, v118
	v_mul_f32_e64 v53, v53, v118
	v_pk_mul_f32 v[50:51], v[50:51], v[118:119] op_sel_hi:[1,0]
	v_pk_mul_f32 v[48:49], v[48:49], v[118:119] op_sel_hi:[1,0]
	s_waitcnt lgkmcnt(11)
	v_mfma_f32_16x16x32_bf16 v[128:131], v[218:221], v[104:107], v[186:189]
	v_mul_f32_e64 v46, v46, v118
	v_mul_f32_e64 v47, v47, v118
	v_pk_mul_f32 v[44:45], v[44:45], v[118:119] op_sel_hi:[1,0]
	v_pk_mul_f32 v[42:43], v[42:43], v[118:119] op_sel_hi:[1,0]
	v_mfma_f32_16x16x32_bf16 v[178:181], v[206:209], v[92:95], v[84:87]
	v_mul_f32_e64 v40, v40, v118
	v_mul_f32_e64 v41, v41, v118
	v_pk_mul_f32 v[62:63], v[62:63], v[118:119] op_sel_hi:[1,0]
	v_pk_mul_f32 v[60:61], v[60:61], v[118:119] op_sel_hi:[1,0]
	v_mfma_f32_16x16x32_bf16 v[88:91], v[214:217], v[92:95], v[88:91]
	v_mul_f32_e64 v58, v58, v118
	v_mul_f32_e64 v59, v59, v118
	v_pk_mul_f32 v[56:57], v[56:57], v[118:119] op_sel_hi:[1,0]
	v_pk_mul_f32 v[66:67], v[66:67], v[118:119] op_sel_hi:[1,0]
	s_waitcnt lgkmcnt(10)
	v_mfma_f32_16x16x32_bf16 v[84:87], v[222:225], v[92:95], v[128:131]
	s_nop 2
	ds_read_b128 v[128:131], v135
	ds_read_b128 v[182:185], v152
	ds_read_b128 v[186:189], v153
	ds_read_b128 v[190:193], v154
	ds_read_b128 v[206:209], v155
	ds_read_b128 v[210:213], v156
	ds_read_b128 v[214:217], v157
	ds_read_b128 v[218:221], v158
	v_pk_mul_f32 v[64:65], v[64:65], v[118:119] op_sel_hi:[1,0]
	v_pk_mul_f32 v[70:71], v[70:71], v[118:119] op_sel_hi:[1,0]
	s_waitcnt lgkmcnt(14)
	v_mfma_f32_16x16x32_bf16 v[80:83], v[226:229], v[104:107], v[80:83]
	v_mul_f32_e64 v68, v68, v118
	v_mul_f32_e64 v69, v69, v118
	v_mfma_f32_16x16x32_bf16 v[80:83], v[230:233], v[92:95], v[80:83]
	v_mfma_f32_16x16x32_bf16 v[52:55], v[174:177], v[104:107], v[52:55]
	s_waitcnt lgkmcnt(13)
	v_mfma_f32_16x16x32_bf16 v[48:51], v[202:205], v[104:107], v[48:51]
	s_waitcnt lgkmcnt(11)
	v_mfma_f32_16x16x32_bf16 v[44:47], v[238:241], v[104:107], v[44:47]
	s_waitcnt lgkmcnt(9)
	v_mfma_f32_16x16x32_bf16 v[40:43], v[246:249], v[104:107], v[40:43]
	v_mfma_f32_16x16x32_bf16 v[52:55], v[194:197], v[92:95], v[52:55]
	v_mfma_f32_16x16x32_bf16 v[48:51], v[234:237], v[92:95], v[48:51]
	v_mfma_f32_16x16x32_bf16 v[44:47], v[242:245], v[92:95], v[44:47]
	s_waitcnt lgkmcnt(8)
	v_mfma_f32_16x16x32_bf16 v[40:43], v[250:253], v[92:95], v[40:43]
	s_waitcnt lgkmcnt(7)
	v_mfma_f32_16x16x32_bf16 v[60:63], v[128:131], v[104:107], v[60:63]
	s_waitcnt lgkmcnt(5)
	v_mfma_f32_16x16x32_bf16 v[56:59], v[186:189], v[104:107], v[56:59]
	s_waitcnt lgkmcnt(3)
	v_mfma_f32_16x16x32_bf16 v[64:67], v[206:209], v[104:107], v[64:67]
	s_waitcnt lgkmcnt(1)
	v_mfma_f32_16x16x32_bf16 v[68:71], v[214:217], v[104:107], v[68:71]
	v_mfma_f32_16x16x32_bf16 v[60:63], v[182:185], v[92:95], v[60:63]
	v_mfma_f32_16x16x32_bf16 v[56:59], v[190:193], v[92:95], v[56:59]
	v_mfma_f32_16x16x32_bf16 v[64:67], v[210:213], v[92:95], v[64:67]
	s_waitcnt lgkmcnt(0)
	v_mfma_f32_16x16x32_bf16 v[68:71], v[218:221], v[92:95], v[68:71]
	v_mul_f32_e32 v106, v168, v179
	v_pk_mul_f32 v[104:105], v[180:181], v[180:181]
	v_pk_mul_f32 v[92:93], v[178:179], v[178:179]
	v_cvt_pk_bf16_f32 v106, v106, s0
	v_mul_f32_e32 v94, v168, v178
	v_mov_b32_dpp v92, v92 quad_perm:[1,0,3,2] row_mask:0xf bank_mask:0xf bound_ctrl:1
	v_mov_b32_dpp v93, v93 quad_perm:[1,0,3,2] row_mask:0xf bank_mask:0xf bound_ctrl:1
	ds_write_b16 v171, v106 offset:288
	v_mov_b32_dpp v104, v104 quad_perm:[1,0,3,2] row_mask:0xf bank_mask:0xf bound_ctrl:1
	v_mul_f32_e32 v106, v168, v180
	v_mov_b32_dpp v105, v105 quad_perm:[1,0,3,2] row_mask:0xf bank_mask:0xf bound_ctrl:1
	v_cvt_pk_bf16_f32 v94, v94, s0
	v_pk_fma_f32 v[92:93], v[178:179], v[178:179], v[92:93]
	v_cvt_pk_bf16_f32 v106, v106, s0
	v_pk_fma_f32 v[104:105], v[180:181], v[180:181], v[104:105]
	ds_write_b16 v171, v94
	v_mov_b32_dpp v94, v92 quad_perm:[2,3,0,1] row_mask:0xf bank_mask:0xf bound_ctrl:1
	v_mov_b32_dpp v95, v93 quad_perm:[2,3,0,1] row_mask:0xf bank_mask:0xf bound_ctrl:1
	ds_write_b16 v171, v106 offset:576
	v_mov_b32_dpp v106, v104 quad_perm:[2,3,0,1] row_mask:0xf bank_mask:0xf bound_ctrl:1
	v_mov_b32_dpp v107, v105 quad_perm:[2,3,0,1] row_mask:0xf bank_mask:0xf bound_ctrl:1
	v_pk_add_f32 v[92:93], v[92:93], v[94:95]
	v_pk_add_f32 v[104:105], v[104:105], v[106:107]
	s_nop 0
	v_mov_b32_dpp v94, v92 row_half_mirror row_mask:0xf bank_mask:0xf bound_ctrl:1
	v_mov_b32_dpp v95, v93 row_half_mirror row_mask:0xf bank_mask:0xf bound_ctrl:1
	v_mov_b32_dpp v106, v104 row_half_mirror row_mask:0xf bank_mask:0xf bound_ctrl:1
	v_mov_b32_dpp v107, v105 row_half_mirror row_mask:0xf bank_mask:0xf bound_ctrl:1
	v_pk_add_f32 v[92:93], v[92:93], v[94:95]
	v_pk_add_f32 v[128:129], v[104:105], v[106:107]
	v_mul_f32_e32 v104, v168, v181
	v_mov_b32_dpp v94, v92 row_mirror row_mask:0xf bank_mask:0xf bound_ctrl:1
	v_mov_b32_dpp v95, v93 row_mirror row_mask:0xf bank_mask:0xf bound_ctrl:1
	v_mov_b32_dpp v130, v128 row_mirror row_mask:0xf bank_mask:0xf bound_ctrl:1
	v_mov_b32_dpp v131, v129 row_mirror row_mask:0xf bank_mask:0xf bound_ctrl:1
	v_cvt_pk_bf16_f32 v104, v104, s0
	ds_write_b16 v171, v104 offset:864
	s_and_saveexec_b64 s[10:11], s[4:5]
	v_pk_add_f32 v[106:107], v[128:129], v[130:131]
	v_pk_add_f32 v[104:105], v[92:93], v[94:95]
	ds_write_b128 v169, v[104:107]
	s_or_b64 exec, exec, s[10:11]
	v_pk_mul_f32 v[92:93], v[88:89], v[88:89]
	v_mul_f32_e32 v94, v168, v88
	v_pk_mul_f32 v[104:105], v[90:91], v[90:91]
	v_mov_b32_dpp v92, v92 quad_perm:[1,0,3,2] row_mask:0xf bank_mask:0xf bound_ctrl:1
	v_mov_b32_dpp v93, v93 quad_perm:[1,0,3,2] row_mask:0xf bank_mask:0xf bound_ctrl:1
	v_pk_fma_f32 v[92:93], v[88:89], v[88:89], v[92:93]
	v_mul_f32_e32 v88, v168, v89
	v_mul_f32_e32 v89, v168, v90
	v_cvt_pk_bf16_f32 v88, v88, s0
	v_cvt_pk_bf16_f32 v89, v89, s0
	ds_write_b16 v171, v88 offset:4896
	v_mov_b32_dpp v88, v104 quad_perm:[1,0,3,2] row_mask:0xf bank_mask:0xf bound_ctrl:1
	ds_write_b16 v171, v89 offset:5184
	v_mov_b32_dpp v89, v105 quad_perm:[1,0,3,2] row_mask:0xf bank_mask:0xf bound_ctrl:1
	v_cvt_pk_bf16_f32 v94, v94, s0
	v_pk_fma_f32 v[88:89], v[90:91], v[90:91], v[88:89]
	ds_write_b16 v171, v94 offset:4608
	v_mov_b32_dpp v94, v92 quad_perm:[2,3,0,1] row_mask:0xf bank_mask:0xf bound_ctrl:1
	v_mov_b32_dpp v95, v93 quad_perm:[2,3,0,1] row_mask:0xf bank_mask:0xf bound_ctrl:1
	v_mov_b32_dpp v104, v88 quad_perm:[2,3,0,1] row_mask:0xf bank_mask:0xf bound_ctrl:1
	v_mov_b32_dpp v105, v89 quad_perm:[2,3,0,1] row_mask:0xf bank_mask:0xf bound_ctrl:1
	v_pk_add_f32 v[92:93], v[92:93], v[94:95]
	v_pk_add_f32 v[88:89], v[88:89], v[104:105]
	v_mul_f32_e32 v90, v168, v91
	v_mov_b32_dpp v94, v92 row_half_mirror row_mask:0xf bank_mask:0xf bound_ctrl:1
	v_mov_b32_dpp v95, v93 row_half_mirror row_mask:0xf bank_mask:0xf bound_ctrl:1
	v_mov_b32_dpp v104, v88 row_half_mirror row_mask:0xf bank_mask:0xf bound_ctrl:1
	v_mov_b32_dpp v105, v89 row_half_mirror row_mask:0xf bank_mask:0xf bound_ctrl:1
	v_pk_add_f32 v[92:93], v[92:93], v[94:95]
	v_pk_add_f32 v[88:89], v[88:89], v[104:105]
	v_cvt_pk_bf16_f32 v90, v90, s0
	v_mov_b32_dpp v94, v92 row_mirror row_mask:0xf bank_mask:0xf bound_ctrl:1
	v_mov_b32_dpp v95, v93 row_mirror row_mask:0xf bank_mask:0xf bound_ctrl:1
	v_mov_b32_dpp v128, v88 row_mirror row_mask:0xf bank_mask:0xf bound_ctrl:1
	v_mov_b32_dpp v129, v89 row_mirror row_mask:0xf bank_mask:0xf bound_ctrl:1
	ds_write_b16 v171, v90 offset:5472
	s_and_saveexec_b64 s[10:11], s[4:5]
	v_pk_add_f32 v[90:91], v[88:89], v[128:129]
	v_pk_add_f32 v[88:89], v[92:93], v[94:95]
	ds_write_b128 v169, v[88:91] offset:64
	s_or_b64 exec, exec, s[10:11]
	v_pk_mul_f32 v[88:89], v[84:85], v[84:85]
	v_mul_f32_e32 v90, v168, v84
	v_pk_mul_f32 v[92:93], v[86:87], v[86:87]
	v_mov_b32_dpp v88, v88 quad_perm:[1,0,3,2] row_mask:0xf bank_mask:0xf bound_ctrl:1
	v_mov_b32_dpp v89, v89 quad_perm:[1,0,3,2] row_mask:0xf bank_mask:0xf bound_ctrl:1
	v_pk_fma_f32 v[88:89], v[84:85], v[84:85], v[88:89]
	v_mul_f32_e32 v84, v168, v85
	v_mul_f32_e32 v85, v168, v86
	v_cvt_pk_bf16_f32 v84, v84, s0
	v_cvt_pk_bf16_f32 v85, v85, s0
	ds_write_b16 v171, v84 offset:9504
	v_mov_b32_dpp v84, v92 quad_perm:[1,0,3,2] row_mask:0xf bank_mask:0xf bound_ctrl:1
	ds_write_b16 v171, v85 offset:9792
	v_mov_b32_dpp v85, v93 quad_perm:[1,0,3,2] row_mask:0xf bank_mask:0xf bound_ctrl:1
	v_cvt_pk_bf16_f32 v90, v90, s0
	v_pk_fma_f32 v[84:85], v[86:87], v[86:87], v[84:85]
	ds_write_b16 v171, v90 offset:9216
	v_mov_b32_dpp v90, v88 quad_perm:[2,3,0,1] row_mask:0xf bank_mask:0xf bound_ctrl:1
	v_mov_b32_dpp v91, v89 quad_perm:[2,3,0,1] row_mask:0xf bank_mask:0xf bound_ctrl:1
	v_mov_b32_dpp v92, v84 quad_perm:[2,3,0,1] row_mask:0xf bank_mask:0xf bound_ctrl:1
	v_mov_b32_dpp v93, v85 quad_perm:[2,3,0,1] row_mask:0xf bank_mask:0xf bound_ctrl:1
	v_pk_add_f32 v[88:89], v[88:89], v[90:91]
	v_pk_add_f32 v[84:85], v[84:85], v[92:93]
	v_mul_f32_e32 v86, v168, v87
	v_mov_b32_dpp v90, v88 row_half_mirror row_mask:0xf bank_mask:0xf bound_ctrl:1
	v_mov_b32_dpp v91, v89 row_half_mirror row_mask:0xf bank_mask:0xf bound_ctrl:1
	v_mov_b32_dpp v92, v84 row_half_mirror row_mask:0xf bank_mask:0xf bound_ctrl:1
	v_mov_b32_dpp v93, v85 row_half_mirror row_mask:0xf bank_mask:0xf bound_ctrl:1
	v_pk_add_f32 v[88:89], v[88:89], v[90:91]
	v_pk_add_f32 v[84:85], v[84:85], v[92:93]
	v_cvt_pk_bf16_f32 v86, v86, s0
	v_mov_b32_dpp v90, v88 row_mirror row_mask:0xf bank_mask:0xf bound_ctrl:1
	v_mov_b32_dpp v91, v89 row_mirror row_mask:0xf bank_mask:0xf bound_ctrl:1
	v_mov_b32_dpp v92, v84 row_mirror row_mask:0xf bank_mask:0xf bound_ctrl:1
	v_mov_b32_dpp v93, v85 row_mirror row_mask:0xf bank_mask:0xf bound_ctrl:1
	ds_write_b16 v171, v86 offset:10080
	s_and_saveexec_b64 s[10:11], s[4:5]
	v_pk_add_f32 v[86:87], v[84:85], v[92:93]
	v_pk_add_f32 v[84:85], v[88:89], v[90:91]
	ds_write_b128 v169, v[84:87] offset:128
	s_or_b64 exec, exec, s[10:11]
	v_pk_mul_f32 v[84:85], v[80:81], v[80:81]
	v_mul_f32_e32 v86, v168, v80
	v_pk_mul_f32 v[88:89], v[82:83], v[82:83]
	v_mov_b32_dpp v84, v84 quad_perm:[1,0,3,2] row_mask:0xf bank_mask:0xf bound_ctrl:1
	v_mov_b32_dpp v85, v85 quad_perm:[1,0,3,2] row_mask:0xf bank_mask:0xf bound_ctrl:1
	v_pk_fma_f32 v[84:85], v[80:81], v[80:81], v[84:85]
	v_mul_f32_e32 v80, v168, v81
	v_mul_f32_e32 v81, v168, v82
	v_cvt_pk_bf16_f32 v80, v80, s0
	v_cvt_pk_bf16_f32 v81, v81, s0
	ds_write_b16 v171, v80 offset:14112
	v_mov_b32_dpp v80, v88 quad_perm:[1,0,3,2] row_mask:0xf bank_mask:0xf bound_ctrl:1
	ds_write_b16 v171, v81 offset:14400
	v_mov_b32_dpp v81, v89 quad_perm:[1,0,3,2] row_mask:0xf bank_mask:0xf bound_ctrl:1
	v_cvt_pk_bf16_f32 v86, v86, s0
	v_pk_fma_f32 v[80:81], v[82:83], v[82:83], v[80:81]
	ds_write_b16 v171, v86 offset:13824
	v_mov_b32_dpp v86, v84 quad_perm:[2,3,0,1] row_mask:0xf bank_mask:0xf bound_ctrl:1
	v_mov_b32_dpp v87, v85 quad_perm:[2,3,0,1] row_mask:0xf bank_mask:0xf bound_ctrl:1
	v_mov_b32_dpp v88, v80 quad_perm:[2,3,0,1] row_mask:0xf bank_mask:0xf bound_ctrl:1
	v_mov_b32_dpp v89, v81 quad_perm:[2,3,0,1] row_mask:0xf bank_mask:0xf bound_ctrl:1
	v_pk_add_f32 v[84:85], v[84:85], v[86:87]
	v_pk_add_f32 v[80:81], v[80:81], v[88:89]
	v_mul_f32_e32 v82, v168, v83
	v_mov_b32_dpp v86, v84 row_half_mirror row_mask:0xf bank_mask:0xf bound_ctrl:1
	v_mov_b32_dpp v87, v85 row_half_mirror row_mask:0xf bank_mask:0xf bound_ctrl:1
	v_mov_b32_dpp v88, v80 row_half_mirror row_mask:0xf bank_mask:0xf bound_ctrl:1
	v_mov_b32_dpp v89, v81 row_half_mirror row_mask:0xf bank_mask:0xf bound_ctrl:1
	v_pk_add_f32 v[84:85], v[84:85], v[86:87]
	v_pk_add_f32 v[80:81], v[80:81], v[88:89]
	v_cvt_pk_bf16_f32 v82, v82, s0
	v_mov_b32_dpp v86, v84 row_mirror row_mask:0xf bank_mask:0xf bound_ctrl:1
	v_mov_b32_dpp v87, v85 row_mirror row_mask:0xf bank_mask:0xf bound_ctrl:1
	v_mov_b32_dpp v88, v80 row_mirror row_mask:0xf bank_mask:0xf bound_ctrl:1
	v_mov_b32_dpp v89, v81 row_mirror row_mask:0xf bank_mask:0xf bound_ctrl:1
	ds_write_b16 v171, v82 offset:14688
	s_and_saveexec_b64 s[10:11], s[4:5]
	v_pk_add_f32 v[82:83], v[80:81], v[88:89]
	v_pk_add_f32 v[80:81], v[84:85], v[86:87]
	ds_write_b128 v169, v[80:83] offset:192
	s_or_b64 exec, exec, s[10:11]
	s_andn2_b64 vcc, exec, s[8:9]
	s_waitcnt lgkmcnt(0)
	s_barrier
	s_cbranch_vccnz .LBB0_708
	s_waitcnt vmcnt(2)
	v_mov_b32_e32 v118, v172
	ds_write_b128 v164, v[0:3]
	ds_write_b128 v164, v[4:7] offset:16
	ds_write_b128 v164, v[8:11] offset:18432
	ds_write_b128 v164, v[12:15] offset:18448
	ds_write_b128 v164, v[16:19] offset:36864
	ds_write_b128 v164, v[20:23] offset:36880
	ds_write_b128 v165, v[32:35] offset:55296
	ds_write_b128 v165, v[36:39] offset:55312
	ds_write_b128 v166, v[24:27]
	ds_write_b128 v167, v[28:31]
	s_branch .LBB0_708
